# LRU: conv taps/bias read from LDS once per unit into spare registers instead of every iteration
# speedup vs baseline: 1.0010x; 1.0010x over previous
.LBB0_363:
	s_or_b64 exec, exec, s[72:73]
	s_waitcnt vmcnt(62)
	v_cvt_pk_bf16_f32 v48, v0, v1
	s_waitcnt vmcnt(0)
	v_mul_f32_e32 v0, 0xbfb8aa3b, v129
	v_cvt_pk_bf16_f32 v49, v2, v3
	v_exp_f32_e32 v2, v0
	v_cvt_pk_bf16_f32 v50, v4, v5
	v_cvt_pk_bf16_f32 v51, v6, v7
	v_cvt_pk_bf16_f32 v52, v8, v13
	v_add_f32_e32 v3, 1.0, v2
	v_add_f32_e32 v0, -1.0, v3
	v_sub_f32_e32 v1, v0, v3
	v_add_f32_e32 v1, 1.0, v1
	v_sub_f32_e32 v0, v2, v0
	v_add_f32_e32 v4, v0, v1
	v_frexp_mant_f32_e32 v5, v3
	v_cvt_f64_f32_e32 v[0:1], v3
	v_frexp_exp_i32_f64_e32 v0, v[0:1]
	v_cmp_gt_f32_e32 vcc, s87, v5
	v_cvt_pk_bf16_f32 v53, v9, v14
	v_cvt_pk_bf16_f32 v54, v10, v15
	v_subbrev_co_u32_e32 v0, vcc, 0, v0, vcc
	v_sub_u32_e32 v1, 0, v0
	v_ldexp_f32 v3, v3, v1
	v_ldexp_f32 v1, v4, v1
	v_add_f32_e32 v4, -1.0, v3
	v_add_f32_e32 v7, 1.0, v3
	v_add_f32_e32 v5, 1.0, v4
	v_add_f32_e32 v8, -1.0, v7
	v_sub_f32_e32 v5, v3, v5
	v_sub_f32_e32 v3, v3, v8
	v_add_f32_e32 v5, v1, v5
	v_add_f32_e32 v1, v1, v3
	v_add_f32_e32 v3, v7, v1
	v_rcp_f32_e32 v8, v3
	v_add_f32_e32 v6, v4, v5
	v_sub_f32_e32 v4, v6, v4
	v_sub_f32_e32 v4, v5, v4
	v_sub_f32_e32 v5, v3, v7
	v_sub_f32_e32 v1, v1, v5
	v_mul_f32_e32 v5, v6, v8
	v_mul_f32_e32 v7, v3, v5
	v_fma_f32 v9, v5, v3, -v7
	v_fmac_f32_e32 v9, v5, v1
	v_add_f32_e32 v10, v7, v9
	v_cvt_pk_bf16_f32 v55, v11, v16
	v_sub_f32_e32 v11, v6, v10
	v_sub_f32_e32 v6, v6, v11
	v_sub_f32_e32 v7, v10, v7
	v_sub_f32_e32 v6, v6, v10
	v_add_f32_e32 v4, v4, v6
	v_sub_f32_e32 v6, v7, v9
	v_add_f32_e32 v4, v6, v4
	v_add_f32_e32 v6, v11, v4
	v_mul_f32_e32 v7, v8, v6
	v_mul_f32_e32 v9, v3, v7
	v_fma_f32 v3, v7, v3, -v9
	v_fmac_f32_e32 v3, v7, v1
	v_sub_f32_e32 v1, v11, v6
	v_add_f32_e32 v1, v4, v1
	v_add_f32_e32 v4, v9, v3
	v_sub_f32_e32 v10, v6, v4
	v_sub_f32_e32 v6, v6, v10
	v_sub_f32_e32 v9, v4, v9
	v_sub_f32_e32 v4, v6, v4
	v_add_f32_e32 v1, v1, v4
	v_sub_f32_e32 v3, v9, v3
	v_cvt_f32_i32_e32 v0, v0
	v_add_f32_e32 v1, v3, v1
	v_add_f32_e32 v3, v5, v7
	v_add_f32_e32 v1, v10, v1
	v_sub_f32_e32 v4, v3, v5
	v_mul_f32_e32 v1, v8, v1
	v_sub_f32_e32 v4, v7, v4
	v_add_f32_e32 v1, v4, v1
	v_mul_f32_e32 v7, 0x3f317218, v0
	v_add_f32_e32 v4, v3, v1
	v_fma_f32 v8, v0, s88, -v7
	v_mul_f32_e32 v5, v4, v4
	v_fmac_f32_e32 v8, 0xb102e308, v0
	v_sub_f32_e32 v0, v4, v3
	v_fmamk_f32 v6, v5, 0x3e9b6dac, v195
	v_sub_f32_e32 v0, v1, v0
	v_add_f32_e32 v1, v7, v8
	v_fmaak_f32 v6, v5, v6, 0x3f2aaada
	v_sub_f32_e32 v3, v1, v7
	v_ldexp_f32 v7, v4, 1
	v_mul_f32_e32 v4, v4, v5
	v_mul_f32_e32 v4, v4, v6
	v_add_f32_e32 v5, v7, v4
	v_sub_f32_e32 v6, v5, v7
	v_ldexp_f32 v0, v0, 1
	v_sub_f32_e32 v4, v4, v6
	v_add_f32_e32 v0, v0, v4
	v_add_f32_e32 v4, v5, v0
	v_sub_f32_e32 v5, v4, v5
	v_sub_f32_e32 v0, v0, v5
	v_add_f32_e32 v5, v1, v4
	s_ashr_i32 s37, s36, 31
	v_sub_f32_e32 v6, v5, v1
	s_and_b32 s72, s91, 15
	v_sub_f32_e32 v7, v5, v6
	s_lshl_b32 s78, s72, 7
	s_lshl_b64 s[36:37], s[36:37], 22
	v_sub_f32_e32 v3, v8, v3
	v_sub_f32_e32 v1, v1, v7
	v_sub_f32_e32 v4, v4, v6
	s_add_u32 s72, s54, s36
	v_add_f32_e32 v1, v4, v1
	v_add_f32_e32 v4, v3, v0
	s_addc_u32 s73, s55, s37
	v_sub_f32_e32 v6, v4, v3
	s_add_u32 s72, s72, s77
	v_sub_f32_e32 v7, v4, v6
	s_addc_u32 s73, s73, 0
	v_sub_f32_e32 v3, v3, v7
	v_sub_f32_e32 v0, v0, v6
	v_add_f32_e32 v1, v4, v1
	s_add_u32 s74, s66, s36
	v_add_f32_e32 v0, v0, v3
	v_add_f32_e32 v3, v5, v1
	s_addc_u32 s75, s67, s37
	v_sub_f32_e32 v4, v3, v5
	s_add_u32 s74, s74, s77
	v_sub_f32_e32 v1, v1, v4
	s_addc_u32 s75, s75, 0
	v_add_f32_e32 v0, v0, v1
	s_add_u32 s36, s44, s36
	v_add_f32_e32 v0, v3, v0
	v_cmp_neq_f32_e32 vcc, s89, v2
	s_addc_u32 s37, s45, s37
	s_add_u32 s94, s36, s77
	v_cndmask_b32_e32 v0, v201, v0, vcc
	v_cmp_ngt_f32_e32 vcc, -1.0, v2
	s_addc_u32 s95, s37, 0
	s_add_u32 s36, s76, s78
	v_cndmask_b32_e32 v0, v202, v0, vcc
	v_cmp_neq_f32_e32 vcc, -1.0, v2
	s_addc_u32 s37, s68, 0
	v_cvt_pk_bf16_f32 v56, v12, v17
	v_cndmask_b32_e32 v0, v203, v0, vcc
	v_cmp_lt_f32_e64 vcc, |v2|, s90
	v_cvt_pk_bf16_f32 v60, v18, v19
	v_cvt_pk_bf16_f32 v57, v20, v21
	v_cndmask_b32_e32 v0, v0, v2, vcc
	v_cvt_pk_bf16_f32 v61, v22, v23
	v_cvt_pk_bf16_f32 v58, v24, v25
	v_cvt_pk_bf16_f32 v62, v26, v27
	v_cvt_pk_bf16_f32 v59, v28, v29
	v_cvt_pk_bf16_f32 v63, v30, v63
	v_cvt_pk_bf16_f32 v64, v31, v64
	v_cvt_pk_bf16_f32 v68, v65, v66
	v_cvt_pk_bf16_f32 v65, v67, v69
	v_cvt_pk_bf16_f32 v69, v70, v71
	v_cvt_pk_bf16_f32 v66, v76, v77
	v_cvt_pk_bf16_f32 v70, v78, v79
	v_cvt_pk_bf16_f32 v67, v80, v81
	v_cvt_pk_bf16_f32 v71, v82, v100
	v_cvt_pk_bf16_f32 v76, v83, v101
	v_cvt_pk_bf16_f32 v80, v102, v103
	v_cvt_pk_bf16_f32 v77, v104, v105
	v_cvt_pk_bf16_f32 v81, v106, v107
	v_cvt_pk_bf16_f32 v78, v108, v109
	v_cvt_pk_bf16_f32 v82, v111, v113
	v_cvt_pk_bf16_f32 v79, v114, v115
	v_cvt_pk_bf16_f32 v83, v110, v112
	v_mul_f32_e32 v125, 0xbfb8aa3b, v125
	v_mul_f32_e32 v127, 0xbfb8aa3b, v127
	s_mov_b32 s93, 0
	v_mul_f32_e32 v129, 0xc138aa3b, v0
	v_lshl_add_u64 v[176:177], v[122:123], 0, s[36:37]
	s_movk_i32 s68, 0xff00
	s_mov_b32 s97, 0
	s_waitcnt lgkmcnt(0)
	s_barrier
	ds_read_b128 v[216:219], v183 offset:1024
	ds_read_b128 v[220:223], v183 offset:1040
	ds_read_b128 v[224:227], v183
	ds_read_b128 v[228:231], v183 offset:16
	ds_read_b128 v[232:235], v183 offset:256
	ds_read_b128 v[236:239], v183 offset:272
	ds_read_b128 v[240:243], v183 offset:512
	ds_read_b128 v[244:247], v183 offset:528
	ds_read_b128 v[248:251], v183 offset:768
	ds_read_b128 v[252:255], v183 offset:784
	s_waitcnt lgkmcnt(0)
	s_branch .LBB0_366

.LBB0_366:
	s_cmp_lt_u32 s97, 5
	s_cbranch_scc1 .Llru_vm0
	s_cmp_eq_u32 s97, 20
	s_cbranch_scc1 .Llru_vm0
	s_waitcnt vmcnt(2)
	s_branch .Llru_vm1

.Llru_vm1:
	v_lshlrev_b32_e32 v34, 16, v36
	v_and_b32_e32 v35, 0xffff0000, v36
	v_pk_fma_f32 v[34:35], v[224:225], v[34:35], v[216:217]
	v_lshlrev_b32_e32 v108, 16, v40
	v_and_b32_e32 v109, 0xffff0000, v40
	v_pk_fma_f32 v[34:35], v[232:233], v[108:109], v[34:35]
	v_lshlrev_b32_e32 v108, 16, v44
	v_and_b32_e32 v109, 0xffff0000, v44
	v_pk_fma_f32 v[34:35], v[240:241], v[108:109], v[34:35]
	v_lshlrev_b32_e32 v108, 16, v72
	v_and_b32_e32 v109, 0xffff0000, v72
	v_pk_fma_f32 v[108:109], v[248:249], v[108:109], v[34:35]
	v_lshlrev_b32_e32 v34, 16, v37
	v_and_b32_e32 v35, 0xffff0000, v37
	v_pk_fma_f32 v[34:35], v[226:227], v[34:35], v[218:219]
	v_lshlrev_b32_e32 v110, 16, v41
	v_and_b32_e32 v111, 0xffff0000, v41
	v_pk_fma_f32 v[34:35], v[234:235], v[110:111], v[34:35]
	v_lshlrev_b32_e32 v110, 16, v45
	v_and_b32_e32 v111, 0xffff0000, v45
	v_pk_fma_f32 v[34:35], v[242:243], v[110:111], v[34:35]
	v_lshlrev_b32_e32 v110, 16, v73
	v_and_b32_e32 v111, 0xffff0000, v73
	v_pk_fma_f32 v[110:111], v[250:251], v[110:111], v[34:35]
	v_lshlrev_b32_e32 v34, 16, v38
	v_and_b32_e32 v35, 0xffff0000, v38
	v_pk_fma_f32 v[34:35], v[228:229], v[34:35], v[220:221]
	v_lshlrev_b32_e32 v112, 16, v42
	v_and_b32_e32 v113, 0xffff0000, v42
	v_pk_fma_f32 v[34:35], v[236:237], v[112:113], v[34:35]
	v_lshlrev_b32_e32 v112, 16, v46
	v_and_b32_e32 v113, 0xffff0000, v46
	v_pk_fma_f32 v[34:35], v[244:245], v[112:113], v[34:35]
	v_lshlrev_b32_e32 v112, 16, v74
	v_and_b32_e32 v113, 0xffff0000, v74
	v_pk_fma_f32 v[112:113], v[252:253], v[112:113], v[34:35]
	v_lshlrev_b32_e32 v34, 16, v39
	v_and_b32_e32 v35, 0xffff0000, v39
	v_pk_fma_f32 v[34:35], v[230:231], v[34:35], v[222:223]
	v_lshlrev_b32_e32 v114, 16, v43
	v_and_b32_e32 v115, 0xffff0000, v43
	v_pk_fma_f32 v[34:35], v[238:239], v[114:115], v[34:35]
	v_lshlrev_b32_e32 v114, 16, v47
	v_and_b32_e32 v115, 0xffff0000, v47
	v_pk_fma_f32 v[34:35], v[246:247], v[114:115], v[34:35]
	v_lshlrev_b32_e32 v114, 16, v75
	v_and_b32_e32 v115, 0xffff0000, v75
	v_pk_fma_f32 v[114:115], v[254:255], v[114:115], v[34:35]
	v_lshlrev_b32_e32 v34, 16, v84
	v_and_b32_e32 v35, 0xffff0000, v84
	v_pk_fma_f32 v[0:1], v[224:225], v[34:35], v[216:217]
	v_lshlrev_b32_e32 v8, 16, v88
	v_and_b32_e32 v9, 0xffff0000, v88
	v_pk_fma_f32 v[0:1], v[232:233], v[8:9], v[0:1]
	v_lshlrev_b32_e32 v8, 16, v92
	v_and_b32_e32 v9, 0xffff0000, v92
	v_pk_fma_f32 v[0:1], v[240:241], v[8:9], v[0:1]
	v_lshlrev_b32_e32 v8, 16, v96
	v_and_b32_e32 v9, 0xffff0000, v96
	v_pk_fma_f32 v[0:1], v[248:249], v[8:9], v[0:1]
	v_lshlrev_b32_e32 v8, 16, v85
	v_and_b32_e32 v9, 0xffff0000, v85
	v_pk_fma_f32 v[2:3], v[226:227], v[8:9], v[218:219]
	v_lshlrev_b32_e32 v8, 16, v89
	v_and_b32_e32 v9, 0xffff0000, v89
	v_pk_fma_f32 v[2:3], v[234:235], v[8:9], v[2:3]
	v_lshlrev_b32_e32 v8, 16, v93
	v_and_b32_e32 v9, 0xffff0000, v93
	v_pk_fma_f32 v[2:3], v[242:243], v[8:9], v[2:3]
	v_lshlrev_b32_e32 v8, 16, v97
	v_and_b32_e32 v9, 0xffff0000, v97
	v_pk_fma_f32 v[2:3], v[250:251], v[8:9], v[2:3]
	v_lshlrev_b32_e32 v8, 16, v86
	v_and_b32_e32 v9, 0xffff0000, v86
	v_pk_fma_f32 v[4:5], v[228:229], v[8:9], v[220:221]
	v_lshlrev_b32_e32 v8, 16, v90
	v_and_b32_e32 v9, 0xffff0000, v90
	v_pk_fma_f32 v[4:5], v[236:237], v[8:9], v[4:5]
	v_lshlrev_b32_e32 v8, 16, v94
	v_and_b32_e32 v9, 0xffff0000, v94
	v_pk_fma_f32 v[4:5], v[244:245], v[8:9], v[4:5]
	v_lshlrev_b32_e32 v8, 16, v98
	v_and_b32_e32 v9, 0xffff0000, v98
	v_pk_fma_f32 v[4:5], v[252:253], v[8:9], v[4:5]
	v_lshlrev_b32_e32 v8, 16, v87
	v_and_b32_e32 v9, 0xffff0000, v87
	v_pk_fma_f32 v[6:7], v[230:231], v[8:9], v[222:223]
	v_lshlrev_b32_e32 v8, 16, v91
	v_and_b32_e32 v9, 0xffff0000, v91
	v_pk_fma_f32 v[6:7], v[238:239], v[8:9], v[6:7]
	v_lshlrev_b32_e32 v8, 16, v95
	v_and_b32_e32 v9, 0xffff0000, v95
	v_pk_fma_f32 v[6:7], v[246:247], v[8:9], v[6:7]
	v_lshlrev_b32_e32 v8, 16, v99
	v_and_b32_e32 v9, 0xffff0000, v99
	v_pk_fma_f32 v[6:7], v[254:255], v[8:9], v[6:7]
	v_cvt_pk_bf16_f32 v8, v108, v109
	v_cvt_pk_bf16_f32 v9, v110, v111
	v_cvt_pk_bf16_f32 v10, v112, v113
	v_cvt_pk_bf16_f32 v11, v114, v115
	s_add_i32 s96, s97, 1
	ds_write_b128 v191, v[108:111]
	ds_write_b128 v191, v[112:115] offset:16
	ds_write_b128 v196, v[8:11] offset:16384
	ds_write_b128 v191, v[0:3] offset:59392
	ds_write_b128 v191, v[4:7] offset:59408
	v_cvt_pk_bf16_f32 v0, v0, v1
	v_cvt_pk_bf16_f32 v1, v2, v3
	v_cvt_pk_bf16_f32 v2, v4, v5
	v_cvt_pk_bf16_f32 v3, v6, v7
	s_cmpk_eq_i32 s68, 0x7c0
	ds_write_b128 v197, v[0:3]
	s_cbranch_scc1 .LBB0_394
	s_and_b32 s36, s96, 0x7b
	s_cmp_lg_u32 s36, 0
	s_cselect_b64 s[36:37], -1, 0
	s_and_b32 s76, s96, 0x5f
	s_cmp_lg_u32 s76, 3
	s_cselect_b64 s[76:77], -1, 0
	s_and_b64 s[36:37], s[36:37], s[76:77]
	s_and_b64 vcc, exec, s[36:37]
	s_cbranch_vccnz .LBB0_375
	s_cmp_lt_u32 s97, 3
	v_add_u32_e32 v0, s68, v180
	s_cselect_b32 s76, 0, 0x100
	s_cselect_b32 s77, s86, 0x900
	v_add_u32_e32 v1, 0x13f, v0
	v_mov_b32_e32 v40, 0
	v_mov_b32_e32 v41, v32
	v_cmp_le_i32_e32 vcc, s76, v1
	v_cmp_gt_i32_e64 s[36:37], s77, v1
	v_mov_b32_e32 v42, v32
	v_mov_b32_e32 v43, v32
	v_mov_b64_e32 v[36:37], v[40:41]
	s_and_b64 s[78:79], vcc, s[36:37]
	v_mov_b64_e32 v[38:39], v[42:43]
	s_and_saveexec_b64 s[36:37], s[78:79]
	s_cbranch_execz .LBB0_370
	global_load_dwordx4 v[36:39], v[176:177], off
